# wo residual epilogue: 128 serialized load/wait/RMW per thread re-issued as 4 batches of 32 (two in flight), same math
# speedup vs baseline: 1.0255x; 1.0243x over previous
.LBB0_944:
	s_add_i32 s3, s1, 1
	s_cmp_lt_u32 s1, 15
	s_cselect_b32 s1, s3, s1
	s_lshl_b32 s12, s1, 6
	s_lshl_b64 s[10:11], s[12:13], 1
	s_barrier
	s_waitcnt vmcnt(0)
	ds_write_b128 v204, v[174:177]
	ds_write_b128 v204, v[170:173] offset:4608
	ds_write_b128 v204, v[166:169] offset:9216
	ds_write_b128 v204, v[162:165] offset:13824
	ds_write_b128 v204, v[158:161] offset:18432
	ds_write_b128 v204, v[154:157] offset:23040
	ds_write_b128 v204, v[150:153] offset:27648
	ds_write_b128 v204, v[146:149] offset:32256
	ds_write_b128 v204, v[142:145] offset:36864
	ds_write_b128 v204, v[134:137] offset:41472
	ds_write_b128 v204, v[130:133] offset:46080
	ds_write_b128 v204, v[138:141] offset:50688
	v_lshl_add_u64 v[130:131], v[178:179], 0, s[10:11]
	s_add_u32 s100, s10, 0x10000
	s_addc_u32 s101, s11, 0
	v_lshl_add_u64 v[132:133], v[178:179], 0, s[100:101]
	s_add_u32 s100, s100, 0x10000
	s_addc_u32 s101, s101, 0
	v_lshl_add_u64 v[134:135], v[178:179], 0, s[100:101]
	s_add_u32 s100, s100, 0x10000
	s_addc_u32 s101, s101, 0
	v_lshl_add_u64 v[136:137], v[178:179], 0, s[100:101]
	s_add_u32 s100, s100, 0x10000
	s_addc_u32 s101, s101, 0
	v_lshl_add_u64 v[138:139], v[178:179], 0, s[100:101]
	s_add_u32 s100, s100, 0x10000
	s_addc_u32 s101, s101, 0
	v_lshl_add_u64 v[140:141], v[178:179], 0, s[100:101]
	s_add_u32 s100, s100, 0x10000
	s_addc_u32 s101, s101, 0
	v_lshl_add_u64 v[142:143], v[178:179], 0, s[100:101]
	s_add_u32 s100, s100, 0x10000
	s_addc_u32 s101, s101, 0
	v_lshl_add_u64 v[144:145], v[178:179], 0, s[100:101]
	s_waitcnt lgkmcnt(0)
	s_barrier
	v_lshl_add_u64 v[224:225], v[180:181], 0, s[10:11]
	s_add_u32 s100, s10, 0x10000
	s_addc_u32 s101, s11, 0
	v_lshl_add_u64 v[226:227], v[180:181], 0, s[100:101]
	s_add_u32 s100, s100, 0x10000
	s_addc_u32 s101, s101, 0
	v_lshl_add_u64 v[228:229], v[180:181], 0, s[100:101]
	s_add_u32 s100, s100, 0x10000
	s_addc_u32 s101, s101, 0
	v_lshl_add_u64 v[230:231], v[180:181], 0, s[100:101]
	global_load_dwordx4 v[174:177], v[130:131], off
	global_load_dwordx4 v[170:173], v[132:133], off
	global_load_dwordx4 v[166:169], v[134:135], off
	global_load_dwordx4 v[162:165], v[136:137], off
	global_load_dwordx4 v[158:161], v[138:139], off
	global_load_dwordx4 v[154:157], v[140:141], off
	global_load_dwordx4 v[150:153], v[142:143], off
	global_load_dwordx4 v[146:149], v[144:145], off
	global_load_dwordx4 v[142:145], v[224:225], off
	global_load_dwordx4 v[134:137], v[226:227], off
	global_load_dwordx4 v[130:133], v[228:229], off
	global_load_dwordx4 v[138:141], v[230:231], off
	ds_read_b128 v[224:227], v182
	ds_read_b128 v[228:231], v183 offset:36864
	ds_read_b128 v[232:235], v183 offset:41472
	ds_read_b128 v[184:187], v182 offset:4608
	ds_read_b128 v[236:239], v183 offset:46080
	ds_read_b128 v[240:243], v183 offset:50688
	s_waitcnt lgkmcnt(4)
	v_mfma_f32_32x32x16_bf16 v[114:129], v[224:227], v[228:231], v[114:129]
	ds_read_b128 v[188:191], v183 offset:36896
	ds_read_b128 v[192:195], v183 offset:41504
	s_waitcnt lgkmcnt(5)
	v_mfma_f32_32x32x16_bf16 v[82:97], v[224:227], v[232:235], v[82:97]
	ds_read_b128 v[196:199], v183 offset:46112
	ds_read_b128 v[200:203], v183 offset:50720
	s_waitcnt lgkmcnt(5)
	v_mfma_f32_32x32x16_bf16 v[98:113], v[224:227], v[236:239], v[98:113]
	s_waitcnt lgkmcnt(4)
	v_mfma_f32_32x32x16_bf16 v[66:81], v[224:227], v[240:243], v[66:81]
	ds_read_b128 v[224:227], v182 offset:32
	v_mfma_f32_32x32x16_bf16 v[50:65], v[184:187], v[228:231], v[50:65]
	v_mfma_f32_32x32x16_bf16 v[16:31], v[184:187], v[232:235], v[16:31]
	v_mfma_f32_32x32x16_bf16 v[34:49], v[184:187], v[236:239], v[34:49]
	v_mfma_f32_32x32x16_bf16 v[0:15], v[184:187], v[240:243], v[0:15]
	ds_read_b128 v[184:187], v182 offset:4640
	s_waitcnt lgkmcnt(1)
	v_mfma_f32_32x32x16_bf16 v[114:129], v[224:227], v[188:191], v[114:129]
	ds_read_b128 v[228:231], v183 offset:36928
	ds_read_b128 v[232:235], v183 offset:41536
	v_mfma_f32_32x32x16_bf16 v[82:97], v[224:227], v[192:195], v[82:97]
	ds_read_b128 v[236:239], v183 offset:46144
	ds_read_b128 v[240:243], v183 offset:50752
	v_mfma_f32_32x32x16_bf16 v[98:113], v[224:227], v[196:199], v[98:113]
	v_mfma_f32_32x32x16_bf16 v[66:81], v[224:227], v[200:203], v[66:81]
	ds_read_b128 v[224:227], v182 offset:64
	s_waitcnt lgkmcnt(5)
	v_mfma_f32_32x32x16_bf16 v[50:65], v[184:187], v[188:191], v[50:65]
	v_mfma_f32_32x32x16_bf16 v[16:31], v[184:187], v[192:195], v[16:31]
	v_mfma_f32_32x32x16_bf16 v[34:49], v[184:187], v[196:199], v[34:49]
	v_mfma_f32_32x32x16_bf16 v[0:15], v[184:187], v[200:203], v[0:15]
	ds_read_b128 v[184:187], v182 offset:4672
	s_waitcnt lgkmcnt(1)
	v_mfma_f32_32x32x16_bf16 v[114:129], v[224:227], v[228:231], v[114:129]
	ds_read_b128 v[188:191], v183 offset:36960
	ds_read_b128 v[192:195], v183 offset:41568
	v_mfma_f32_32x32x16_bf16 v[82:97], v[224:227], v[232:235], v[82:97]
	ds_read_b128 v[196:199], v183 offset:46176
	ds_read_b128 v[200:203], v183 offset:50784
	v_mfma_f32_32x32x16_bf16 v[98:113], v[224:227], v[236:239], v[98:113]
	v_mfma_f32_32x32x16_bf16 v[66:81], v[224:227], v[240:243], v[66:81]
	ds_read_b128 v[224:227], v182 offset:96
	s_waitcnt lgkmcnt(5)
	v_mfma_f32_32x32x16_bf16 v[50:65], v[184:187], v[228:231], v[50:65]
	v_mfma_f32_32x32x16_bf16 v[16:31], v[184:187], v[232:235], v[16:31]
	v_mfma_f32_32x32x16_bf16 v[34:49], v[184:187], v[236:239], v[34:49]
	v_mfma_f32_32x32x16_bf16 v[0:15], v[184:187], v[240:243], v[0:15]
	ds_read_b128 v[184:187], v182 offset:4704
	s_waitcnt lgkmcnt(1)
	v_mfma_f32_32x32x16_bf16 v[114:129], v[224:227], v[188:191], v[114:129]
	v_mfma_f32_32x32x16_bf16 v[82:97], v[224:227], v[192:195], v[82:97]
	v_mfma_f32_32x32x16_bf16 v[98:113], v[224:227], v[196:199], v[98:113]
	v_mfma_f32_32x32x16_bf16 v[66:81], v[224:227], v[200:203], v[66:81]
	s_waitcnt lgkmcnt(0)
	v_mfma_f32_32x32x16_bf16 v[50:65], v[184:187], v[188:191], v[50:65]
	v_mfma_f32_32x32x16_bf16 v[16:31], v[184:187], v[192:195], v[16:31]
	v_mfma_f32_32x32x16_bf16 v[34:49], v[184:187], v[196:199], v[34:49]
	v_mfma_f32_32x32x16_bf16 v[0:15], v[184:187], v[200:203], v[0:15]
	s_mov_b32 s1, s3
	s_cmp_lg_u32 s3, 16
	s_cbranch_scc1 .LBB0_944
	s_lshl_b32 s1, s2, 7
	s_lshr_b32 s2, s9, 24
	s_add_i32 s2, s8, s2
	s_lshr_b32 s2, s2, 8
	s_add_i32 s2, s2, s6
	s_mulk_i32 s2, 0x1800
	v_mov_b32_e32 v32, v206
	s_barrier
	s_ashr_i32 s3, s2, 31
	v_readlane_b32 s36, v248, 46
	s_lshl_b64 s[2:3], s[2:3], 2
	s_waitcnt vmcnt(1)
	v_and_b32_e32 v130, 0xffffffc0, v32
	v_lshrrev_b32_e32 v131, 3, v32
	v_readlane_b32 s40, v248, 50
	v_and_or_b32 v148, v32, 31, s1
	v_and_or_b32 v32, v131, 4, v130
	v_readlane_b32 s41, v248, 51
	s_add_u32 s2, s40, s2
	v_lshl_add_u32 v132, s0, 8, v32
	s_addc_u32 s3, s41, s3
	v_ashrrev_i32_e32 v133, 31, v132
	v_readlane_b32 s48, v248, 58
	v_readlane_b32 s49, v248, 59
	s_add_u32 s2, s2, 0x2000
	v_ashrrev_i32_e32 v149, 31, v148
	v_lshlrev_b64 v[136:137], 12, v[132:133]
	s_addc_u32 s3, s3, 0
	v_lshlrev_b64 v[130:131], 2, v[148:149]
	v_lshl_add_u64 v[136:137], s[48:49], 0, v[136:137]
	v_lshl_add_u64 v[134:135], s[2:3], 0, v[130:131]
	v_lshl_add_u64 v[150:151], v[136:137], 0, v[130:131]
	v_writelane_b32 v251, s12, 29
	v_readlane_b32 s37, v248, 47
	v_readlane_b32 s38, v248, 48
	v_writelane_b32 v251, s13, 30
	v_readlane_b32 s39, v248, 49
	v_readlane_b32 s0, v251, 24
	s_add_i32 s7, s7, s0
	s_cmpk_lt_i32 s7, 0x200
	v_readlane_b32 s42, v248, 52
	v_readlane_b32 s43, v248, 53
	v_readlane_b32 s44, v248, 54
	v_readlane_b32 s45, v248, 55
	v_readlane_b32 s46, v248, 56
	v_readlane_b32 s47, v248, 57
	v_readlane_b32 s50, v248, 60
	v_readlane_b32 s51, v248, 61
	v_readlane_b32 s1, v251, 25
	s_waitcnt vmcnt(0)
	v_lshlrev_b32_e32 v240, 2, v148
	v_lshl_add_u32 v240, v132, 12, v240
	s_nop 2
	global_load_dword v241, v[134:135], off
	global_load_dword v242, v[134:135], off offset:128
	global_load_dword v243, v[134:135], off offset:256
	global_load_dword v151, v[134:135], off offset:384
	v_mov_b32_e32 v232, v240
	v_add_u32_e32 v233, 0x1000, v240
	v_add_u32_e32 v234, 0x2000, v240
	v_add_u32_e32 v235, 0x3000, v240
	v_add_u32_e32 v236, 0x8000, v240
	v_add_u32_e32 v237, 0x9000, v240
	v_add_u32_e32 v238, 0xa000, v240
	v_add_u32_e32 v239, 0xb000, v240
	global_load_dword v138, v232, s[48:49]
	global_load_dword v139, v232, s[48:49] offset:128
	global_load_dword v140, v232, s[48:49] offset:256
	global_load_dword v141, v232, s[48:49] offset:384
	global_load_dword v142, v233, s[48:49]
	global_load_dword v143, v233, s[48:49] offset:128
	global_load_dword v144, v233, s[48:49] offset:256
	global_load_dword v145, v233, s[48:49] offset:384
	global_load_dword v146, v234, s[48:49]
	global_load_dword v147, v234, s[48:49] offset:128
	global_load_dword v152, v234, s[48:49] offset:256
	global_load_dword v153, v234, s[48:49] offset:384
	global_load_dword v154, v235, s[48:49]
	global_load_dword v155, v235, s[48:49] offset:128
	global_load_dword v156, v235, s[48:49] offset:256
	global_load_dword v157, v235, s[48:49] offset:384
	global_load_dword v158, v236, s[48:49]
	global_load_dword v159, v236, s[48:49] offset:128
	global_load_dword v160, v236, s[48:49] offset:256
	global_load_dword v161, v236, s[48:49] offset:384
	global_load_dword v162, v237, s[48:49]
	global_load_dword v163, v237, s[48:49] offset:128
	global_load_dword v164, v237, s[48:49] offset:256
	global_load_dword v165, v237, s[48:49] offset:384
	global_load_dword v166, v238, s[48:49]
	global_load_dword v167, v238, s[48:49] offset:128
	global_load_dword v168, v238, s[48:49] offset:256
	global_load_dword v169, v238, s[48:49] offset:384
	global_load_dword v170, v239, s[48:49]
	global_load_dword v171, v239, s[48:49] offset:128
	global_load_dword v172, v239, s[48:49] offset:256
	global_load_dword v173, v239, s[48:49] offset:384
	v_add_u32_e32 v130, 0x10000, v240
	v_add_u32_e32 v131, 0x11000, v240
	v_add_u32_e32 v132, 0x12000, v240
	v_add_u32_e32 v133, 0x13000, v240
	v_add_u32_e32 v134, 0x18000, v240
	v_add_u32_e32 v135, 0x19000, v240
	v_add_u32_e32 v136, 0x1a000, v240
	v_add_u32_e32 v137, 0x1b000, v240
	global_load_dword v174, v130, s[48:49]
	global_load_dword v175, v130, s[48:49] offset:128
	global_load_dword v176, v130, s[48:49] offset:256
	global_load_dword v177, v130, s[48:49] offset:384
	global_load_dword v184, v131, s[48:49]
	global_load_dword v185, v131, s[48:49] offset:128
	global_load_dword v186, v131, s[48:49] offset:256
	global_load_dword v187, v131, s[48:49] offset:384
	global_load_dword v188, v132, s[48:49]
	global_load_dword v189, v132, s[48:49] offset:128
	global_load_dword v190, v132, s[48:49] offset:256
	global_load_dword v191, v132, s[48:49] offset:384
	global_load_dword v192, v133, s[48:49]
	global_load_dword v193, v133, s[48:49] offset:128
	global_load_dword v194, v133, s[48:49] offset:256
	global_load_dword v195, v133, s[48:49] offset:384
	global_load_dword v196, v134, s[48:49]
	global_load_dword v197, v134, s[48:49] offset:128
	global_load_dword v198, v134, s[48:49] offset:256
	global_load_dword v199, v134, s[48:49] offset:384
	global_load_dword v200, v135, s[48:49]
	global_load_dword v201, v135, s[48:49] offset:128
	global_load_dword v202, v135, s[48:49] offset:256
	global_load_dword v203, v135, s[48:49] offset:384
	global_load_dword v224, v136, s[48:49]
	global_load_dword v225, v136, s[48:49] offset:128
	global_load_dword v226, v136, s[48:49] offset:256
	global_load_dword v227, v136, s[48:49] offset:384
	global_load_dword v228, v137, s[48:49]
	global_load_dword v229, v137, s[48:49] offset:128
	global_load_dword v230, v137, s[48:49] offset:256
	global_load_dword v231, v137, s[48:49] offset:384
	s_waitcnt vmcnt(32)
	v_mul_f32_e32 v138, 0x3fd744fd, v138
	v_mul_f32_e32 v139, 0x3fd744fd, v139
	v_mul_f32_e32 v140, 0x3fd744fd, v140
	v_mul_f32_e32 v141, 0x3fd744fd, v141
	v_mul_f32_e32 v142, 0x3fd744fd, v142
	v_mul_f32_e32 v143, 0x3fd744fd, v143
	v_mul_f32_e32 v144, 0x3fd744fd, v144
	v_mul_f32_e32 v145, 0x3fd744fd, v145
	v_mul_f32_e32 v146, 0x3fd744fd, v146
	v_mul_f32_e32 v147, 0x3fd744fd, v147
	v_mul_f32_e32 v152, 0x3fd744fd, v152
	v_mul_f32_e32 v153, 0x3fd744fd, v153
	v_mul_f32_e32 v154, 0x3fd744fd, v154
	v_mul_f32_e32 v155, 0x3fd744fd, v155
	v_mul_f32_e32 v156, 0x3fd744fd, v156
	v_mul_f32_e32 v157, 0x3fd744fd, v157
	v_mul_f32_e32 v158, 0x3fd744fd, v158
	v_mul_f32_e32 v159, 0x3fd744fd, v159
	v_mul_f32_e32 v160, 0x3fd744fd, v160
	v_mul_f32_e32 v161, 0x3fd744fd, v161
	v_mul_f32_e32 v162, 0x3fd744fd, v162
	v_mul_f32_e32 v163, 0x3fd744fd, v163
	v_mul_f32_e32 v164, 0x3fd744fd, v164
	v_mul_f32_e32 v165, 0x3fd744fd, v165
	v_mul_f32_e32 v166, 0x3fd744fd, v166
	v_mul_f32_e32 v167, 0x3fd744fd, v167
	v_mul_f32_e32 v168, 0x3fd744fd, v168
	v_mul_f32_e32 v169, 0x3fd744fd, v169
	v_mul_f32_e32 v170, 0x3fd744fd, v170
	v_mul_f32_e32 v171, 0x3fd744fd, v171
	v_mul_f32_e32 v172, 0x3fd744fd, v172
	v_mul_f32_e32 v173, 0x3fd744fd, v173
	v_fmac_f32_e32 v138, v114, v241
	v_fmac_f32_e32 v139, v82, v242
	v_fmac_f32_e32 v140, v98, v243
	v_fmac_f32_e32 v141, v66, v151
	v_fmac_f32_e32 v142, v115, v241
	v_fmac_f32_e32 v143, v83, v242
	v_fmac_f32_e32 v144, v99, v243
	v_fmac_f32_e32 v145, v67, v151
	v_fmac_f32_e32 v146, v116, v241
	v_fmac_f32_e32 v147, v84, v242
	v_fmac_f32_e32 v152, v100, v243
	v_fmac_f32_e32 v153, v68, v151
	v_fmac_f32_e32 v154, v117, v241
	v_fmac_f32_e32 v155, v85, v242
	v_fmac_f32_e32 v156, v101, v243
	v_fmac_f32_e32 v157, v69, v151
	v_fmac_f32_e32 v158, v118, v241
	v_fmac_f32_e32 v159, v86, v242
	v_fmac_f32_e32 v160, v102, v243
	v_fmac_f32_e32 v161, v70, v151
	v_fmac_f32_e32 v162, v119, v241
	v_fmac_f32_e32 v163, v87, v242
	v_fmac_f32_e32 v164, v103, v243
	v_fmac_f32_e32 v165, v71, v151
	v_fmac_f32_e32 v166, v120, v241
	v_fmac_f32_e32 v167, v88, v242
	v_fmac_f32_e32 v168, v104, v243
	v_fmac_f32_e32 v169, v72, v151
	v_fmac_f32_e32 v170, v121, v241
	v_fmac_f32_e32 v171, v89, v242
	v_fmac_f32_e32 v172, v105, v243
	v_fmac_f32_e32 v173, v73, v151
	global_store_dword v232, v138, s[48:49]
	global_store_dword v232, v139, s[48:49] offset:128
	global_store_dword v232, v140, s[48:49] offset:256
	global_store_dword v232, v141, s[48:49] offset:384
	global_store_dword v233, v142, s[48:49]
	global_store_dword v233, v143, s[48:49] offset:128
	global_store_dword v233, v144, s[48:49] offset:256
	global_store_dword v233, v145, s[48:49] offset:384
	global_store_dword v234, v146, s[48:49]
	global_store_dword v234, v147, s[48:49] offset:128
	global_store_dword v234, v152, s[48:49] offset:256
	global_store_dword v234, v153, s[48:49] offset:384
	global_store_dword v235, v154, s[48:49]
	global_store_dword v235, v155, s[48:49] offset:128
	global_store_dword v235, v156, s[48:49] offset:256
	global_store_dword v235, v157, s[48:49] offset:384
	global_store_dword v236, v158, s[48:49]
	global_store_dword v236, v159, s[48:49] offset:128
	global_store_dword v236, v160, s[48:49] offset:256
	global_store_dword v236, v161, s[48:49] offset:384
	global_store_dword v237, v162, s[48:49]
	global_store_dword v237, v163, s[48:49] offset:128
	global_store_dword v237, v164, s[48:49] offset:256
	global_store_dword v237, v165, s[48:49] offset:384
	global_store_dword v238, v166, s[48:49]
	global_store_dword v238, v167, s[48:49] offset:128
	global_store_dword v238, v168, s[48:49] offset:256
	global_store_dword v238, v169, s[48:49] offset:384
	global_store_dword v239, v170, s[48:49]
	global_store_dword v239, v171, s[48:49] offset:128
	global_store_dword v239, v172, s[48:49] offset:256
	global_store_dword v239, v173, s[48:49] offset:384
	v_add_u32_e32 v232, 0x20000, v240
	v_add_u32_e32 v233, 0x21000, v240
	v_add_u32_e32 v234, 0x22000, v240
	v_add_u32_e32 v235, 0x23000, v240
	v_add_u32_e32 v236, 0x28000, v240
	v_add_u32_e32 v237, 0x29000, v240
	v_add_u32_e32 v238, 0x2a000, v240
	v_add_u32_e32 v239, 0x2b000, v240
	global_load_dword v138, v232, s[48:49]
	global_load_dword v139, v232, s[48:49] offset:128
	global_load_dword v140, v232, s[48:49] offset:256
	global_load_dword v141, v232, s[48:49] offset:384
	global_load_dword v142, v233, s[48:49]
	global_load_dword v143, v233, s[48:49] offset:128
	global_load_dword v144, v233, s[48:49] offset:256
	global_load_dword v145, v233, s[48:49] offset:384
	global_load_dword v146, v234, s[48:49]
	global_load_dword v147, v234, s[48:49] offset:128
	global_load_dword v152, v234, s[48:49] offset:256
	global_load_dword v153, v234, s[48:49] offset:384
	global_load_dword v154, v235, s[48:49]
	global_load_dword v155, v235, s[48:49] offset:128
	global_load_dword v156, v235, s[48:49] offset:256
	global_load_dword v157, v235, s[48:49] offset:384
	global_load_dword v158, v236, s[48:49]
	global_load_dword v159, v236, s[48:49] offset:128
	global_load_dword v160, v236, s[48:49] offset:256
	global_load_dword v161, v236, s[48:49] offset:384
	global_load_dword v162, v237, s[48:49]
	global_load_dword v163, v237, s[48:49] offset:128
	global_load_dword v164, v237, s[48:49] offset:256
	global_load_dword v165, v237, s[48:49] offset:384
	global_load_dword v166, v238, s[48:49]
	global_load_dword v167, v238, s[48:49] offset:128
	global_load_dword v168, v238, s[48:49] offset:256
	global_load_dword v169, v238, s[48:49] offset:384
	global_load_dword v170, v239, s[48:49]
	global_load_dword v171, v239, s[48:49] offset:128
	global_load_dword v172, v239, s[48:49] offset:256
	global_load_dword v173, v239, s[48:49] offset:384
	s_waitcnt vmcnt(63)
	v_mul_f32_e32 v174, 0x3fd744fd, v174
	v_mul_f32_e32 v175, 0x3fd744fd, v175
	v_mul_f32_e32 v176, 0x3fd744fd, v176
	v_mul_f32_e32 v177, 0x3fd744fd, v177
	v_mul_f32_e32 v184, 0x3fd744fd, v184
	v_mul_f32_e32 v185, 0x3fd744fd, v185
	v_mul_f32_e32 v186, 0x3fd744fd, v186
	v_mul_f32_e32 v187, 0x3fd744fd, v187
	v_mul_f32_e32 v188, 0x3fd744fd, v188
	v_mul_f32_e32 v189, 0x3fd744fd, v189
	v_mul_f32_e32 v190, 0x3fd744fd, v190
	v_mul_f32_e32 v191, 0x3fd744fd, v191
	v_mul_f32_e32 v192, 0x3fd744fd, v192
	v_mul_f32_e32 v193, 0x3fd744fd, v193
	v_mul_f32_e32 v194, 0x3fd744fd, v194
	v_mul_f32_e32 v195, 0x3fd744fd, v195
	v_mul_f32_e32 v196, 0x3fd744fd, v196
	v_mul_f32_e32 v197, 0x3fd744fd, v197
	v_mul_f32_e32 v198, 0x3fd744fd, v198
	v_mul_f32_e32 v199, 0x3fd744fd, v199
	v_mul_f32_e32 v200, 0x3fd744fd, v200
	v_mul_f32_e32 v201, 0x3fd744fd, v201
	v_mul_f32_e32 v202, 0x3fd744fd, v202
	v_mul_f32_e32 v203, 0x3fd744fd, v203
	v_mul_f32_e32 v224, 0x3fd744fd, v224
	v_mul_f32_e32 v225, 0x3fd744fd, v225
	v_mul_f32_e32 v226, 0x3fd744fd, v226
	v_mul_f32_e32 v227, 0x3fd744fd, v227
	v_mul_f32_e32 v228, 0x3fd744fd, v228
	v_mul_f32_e32 v229, 0x3fd744fd, v229
	v_mul_f32_e32 v230, 0x3fd744fd, v230
	v_mul_f32_e32 v231, 0x3fd744fd, v231
	v_fmac_f32_e32 v174, v122, v241
	v_fmac_f32_e32 v175, v90, v242
	v_fmac_f32_e32 v176, v106, v243
	v_fmac_f32_e32 v177, v74, v151
	v_fmac_f32_e32 v184, v123, v241
	v_fmac_f32_e32 v185, v91, v242
	v_fmac_f32_e32 v186, v107, v243
	v_fmac_f32_e32 v187, v75, v151
	v_fmac_f32_e32 v188, v124, v241
	v_fmac_f32_e32 v189, v92, v242
	v_fmac_f32_e32 v190, v108, v243
	v_fmac_f32_e32 v191, v76, v151
	v_fmac_f32_e32 v192, v125, v241
	v_fmac_f32_e32 v193, v93, v242
	v_fmac_f32_e32 v194, v109, v243
	v_fmac_f32_e32 v195, v77, v151
	v_fmac_f32_e32 v196, v126, v241
	v_fmac_f32_e32 v197, v94, v242
	v_fmac_f32_e32 v198, v110, v243
	v_fmac_f32_e32 v199, v78, v151
	v_fmac_f32_e32 v200, v127, v241
	v_fmac_f32_e32 v201, v95, v242
	v_fmac_f32_e32 v202, v111, v243
	v_fmac_f32_e32 v203, v79, v151
	v_fmac_f32_e32 v224, v128, v241
	v_fmac_f32_e32 v225, v96, v242
	v_fmac_f32_e32 v226, v112, v243
	v_fmac_f32_e32 v227, v80, v151
	v_fmac_f32_e32 v228, v129, v241
	v_fmac_f32_e32 v229, v97, v242
	v_fmac_f32_e32 v230, v113, v243
	v_fmac_f32_e32 v231, v81, v151
	global_store_dword v130, v174, s[48:49]
	global_store_dword v130, v175, s[48:49] offset:128
	global_store_dword v130, v176, s[48:49] offset:256
	global_store_dword v130, v177, s[48:49] offset:384
	global_store_dword v131, v184, s[48:49]
	global_store_dword v131, v185, s[48:49] offset:128
	global_store_dword v131, v186, s[48:49] offset:256
	global_store_dword v131, v187, s[48:49] offset:384
	global_store_dword v132, v188, s[48:49]
	global_store_dword v132, v189, s[48:49] offset:128
	global_store_dword v132, v190, s[48:49] offset:256
	global_store_dword v132, v191, s[48:49] offset:384
	global_store_dword v133, v192, s[48:49]
	global_store_dword v133, v193, s[48:49] offset:128
	global_store_dword v133, v194, s[48:49] offset:256
	global_store_dword v133, v195, s[48:49] offset:384
	global_store_dword v134, v196, s[48:49]
	global_store_dword v134, v197, s[48:49] offset:128
	global_store_dword v134, v198, s[48:49] offset:256
	global_store_dword v134, v199, s[48:49] offset:384
	global_store_dword v135, v200, s[48:49]
	global_store_dword v135, v201, s[48:49] offset:128
	global_store_dword v135, v202, s[48:49] offset:256
	global_store_dword v135, v203, s[48:49] offset:384
	global_store_dword v136, v224, s[48:49]
	global_store_dword v136, v225, s[48:49] offset:128
	global_store_dword v136, v226, s[48:49] offset:256
	global_store_dword v136, v227, s[48:49] offset:384
	global_store_dword v137, v228, s[48:49]
	global_store_dword v137, v229, s[48:49] offset:128
	global_store_dword v137, v230, s[48:49] offset:256
	global_store_dword v137, v231, s[48:49] offset:384
	v_add_u32_e32 v130, 0x30000, v240
	v_add_u32_e32 v131, 0x31000, v240
	v_add_u32_e32 v132, 0x32000, v240
	v_add_u32_e32 v133, 0x33000, v240
	v_add_u32_e32 v134, 0x38000, v240
	v_add_u32_e32 v135, 0x39000, v240
	v_add_u32_e32 v136, 0x3a000, v240
	v_add_u32_e32 v137, 0x3b000, v240
	global_load_dword v174, v130, s[48:49]
	global_load_dword v175, v130, s[48:49] offset:128
	global_load_dword v176, v130, s[48:49] offset:256
	global_load_dword v177, v130, s[48:49] offset:384
	global_load_dword v184, v131, s[48:49]
	global_load_dword v185, v131, s[48:49] offset:128
	global_load_dword v186, v131, s[48:49] offset:256
	global_load_dword v187, v131, s[48:49] offset:384
	global_load_dword v188, v132, s[48:49]
	global_load_dword v189, v132, s[48:49] offset:128
	global_load_dword v190, v132, s[48:49] offset:256
	global_load_dword v191, v132, s[48:49] offset:384
	global_load_dword v192, v133, s[48:49]
	global_load_dword v193, v133, s[48:49] offset:128
	global_load_dword v194, v133, s[48:49] offset:256
	global_load_dword v195, v133, s[48:49] offset:384
	global_load_dword v196, v134, s[48:49]
	global_load_dword v197, v134, s[48:49] offset:128
	global_load_dword v198, v134, s[48:49] offset:256
	global_load_dword v199, v134, s[48:49] offset:384
	global_load_dword v200, v135, s[48:49]
	global_load_dword v201, v135, s[48:49] offset:128
	global_load_dword v202, v135, s[48:49] offset:256
	global_load_dword v203, v135, s[48:49] offset:384
	global_load_dword v224, v136, s[48:49]
	global_load_dword v225, v136, s[48:49] offset:128
	global_load_dword v226, v136, s[48:49] offset:256
	global_load_dword v227, v136, s[48:49] offset:384
	global_load_dword v228, v137, s[48:49]
	global_load_dword v229, v137, s[48:49] offset:128
	global_load_dword v230, v137, s[48:49] offset:256
	global_load_dword v231, v137, s[48:49] offset:384
	s_waitcnt vmcnt(63)
	v_mul_f32_e32 v138, 0x3fd744fd, v138
	v_mul_f32_e32 v139, 0x3fd744fd, v139
	v_mul_f32_e32 v140, 0x3fd744fd, v140
	v_mul_f32_e32 v141, 0x3fd744fd, v141
	v_mul_f32_e32 v142, 0x3fd744fd, v142
	v_mul_f32_e32 v143, 0x3fd744fd, v143
	v_mul_f32_e32 v144, 0x3fd744fd, v144
	v_mul_f32_e32 v145, 0x3fd744fd, v145
	v_mul_f32_e32 v146, 0x3fd744fd, v146
	v_mul_f32_e32 v147, 0x3fd744fd, v147
	v_mul_f32_e32 v152, 0x3fd744fd, v152
	v_mul_f32_e32 v153, 0x3fd744fd, v153
	v_mul_f32_e32 v154, 0x3fd744fd, v154
	v_mul_f32_e32 v155, 0x3fd744fd, v155
	v_mul_f32_e32 v156, 0x3fd744fd, v156
	v_mul_f32_e32 v157, 0x3fd744fd, v157
	v_mul_f32_e32 v158, 0x3fd744fd, v158
	v_mul_f32_e32 v159, 0x3fd744fd, v159
	v_mul_f32_e32 v160, 0x3fd744fd, v160
	v_mul_f32_e32 v161, 0x3fd744fd, v161
	v_mul_f32_e32 v162, 0x3fd744fd, v162
	v_mul_f32_e32 v163, 0x3fd744fd, v163
	v_mul_f32_e32 v164, 0x3fd744fd, v164
	v_mul_f32_e32 v165, 0x3fd744fd, v165
	v_mul_f32_e32 v166, 0x3fd744fd, v166
	v_mul_f32_e32 v167, 0x3fd744fd, v167
	v_mul_f32_e32 v168, 0x3fd744fd, v168
	v_mul_f32_e32 v169, 0x3fd744fd, v169
	v_mul_f32_e32 v170, 0x3fd744fd, v170
	v_mul_f32_e32 v171, 0x3fd744fd, v171
	v_mul_f32_e32 v172, 0x3fd744fd, v172
	v_mul_f32_e32 v173, 0x3fd744fd, v173
	v_fmac_f32_e32 v138, v50, v241
	v_fmac_f32_e32 v139, v16, v242
	v_fmac_f32_e32 v140, v34, v243
	v_fmac_f32_e32 v141, v0, v151
	v_fmac_f32_e32 v142, v51, v241
	v_fmac_f32_e32 v143, v17, v242
	v_fmac_f32_e32 v144, v35, v243
	v_fmac_f32_e32 v145, v1, v151
	v_fmac_f32_e32 v146, v52, v241
	v_fmac_f32_e32 v147, v18, v242
	v_fmac_f32_e32 v152, v36, v243
	v_fmac_f32_e32 v153, v2, v151
	v_fmac_f32_e32 v154, v53, v241
	v_fmac_f32_e32 v155, v19, v242
	v_fmac_f32_e32 v156, v37, v243
	v_fmac_f32_e32 v157, v3, v151
	v_fmac_f32_e32 v158, v54, v241
	v_fmac_f32_e32 v159, v20, v242
	v_fmac_f32_e32 v160, v38, v243
	v_fmac_f32_e32 v161, v4, v151
	v_fmac_f32_e32 v162, v55, v241
	v_fmac_f32_e32 v163, v21, v242
	v_fmac_f32_e32 v164, v39, v243
	v_fmac_f32_e32 v165, v5, v151
	v_fmac_f32_e32 v166, v56, v241
	v_fmac_f32_e32 v167, v22, v242
	v_fmac_f32_e32 v168, v40, v243
	v_fmac_f32_e32 v169, v6, v151
	v_fmac_f32_e32 v170, v57, v241
	v_fmac_f32_e32 v171, v23, v242
	v_fmac_f32_e32 v172, v41, v243
	v_fmac_f32_e32 v173, v7, v151
	global_store_dword v232, v138, s[48:49]
	global_store_dword v232, v139, s[48:49] offset:128
	global_store_dword v232, v140, s[48:49] offset:256
	global_store_dword v232, v141, s[48:49] offset:384
	global_store_dword v233, v142, s[48:49]
	global_store_dword v233, v143, s[48:49] offset:128
	global_store_dword v233, v144, s[48:49] offset:256
	global_store_dword v233, v145, s[48:49] offset:384
	global_store_dword v234, v146, s[48:49]
	global_store_dword v234, v147, s[48:49] offset:128
	global_store_dword v234, v152, s[48:49] offset:256
	global_store_dword v234, v153, s[48:49] offset:384
	global_store_dword v235, v154, s[48:49]
	global_store_dword v235, v155, s[48:49] offset:128
	global_store_dword v235, v156, s[48:49] offset:256
	global_store_dword v235, v157, s[48:49] offset:384
	global_store_dword v236, v158, s[48:49]
	global_store_dword v236, v159, s[48:49] offset:128
	global_store_dword v236, v160, s[48:49] offset:256
	global_store_dword v236, v161, s[48:49] offset:384
	global_store_dword v237, v162, s[48:49]
	global_store_dword v237, v163, s[48:49] offset:128
	global_store_dword v237, v164, s[48:49] offset:256
	global_store_dword v237, v165, s[48:49] offset:384
	global_store_dword v238, v166, s[48:49]
	global_store_dword v238, v167, s[48:49] offset:128
	global_store_dword v238, v168, s[48:49] offset:256
	global_store_dword v238, v169, s[48:49] offset:384
	global_store_dword v239, v170, s[48:49]
	global_store_dword v239, v171, s[48:49] offset:128
	global_store_dword v239, v172, s[48:49] offset:256
	global_store_dword v239, v173, s[48:49] offset:384
	s_waitcnt vmcnt(32)
	v_mul_f32_e32 v174, 0x3fd744fd, v174
	v_mul_f32_e32 v175, 0x3fd744fd, v175
	v_mul_f32_e32 v176, 0x3fd744fd, v176
	v_mul_f32_e32 v177, 0x3fd744fd, v177
	v_mul_f32_e32 v184, 0x3fd744fd, v184
	v_mul_f32_e32 v185, 0x3fd744fd, v185
	v_mul_f32_e32 v186, 0x3fd744fd, v186
	v_mul_f32_e32 v187, 0x3fd744fd, v187
	v_mul_f32_e32 v188, 0x3fd744fd, v188
	v_mul_f32_e32 v189, 0x3fd744fd, v189
	v_mul_f32_e32 v190, 0x3fd744fd, v190
	v_mul_f32_e32 v191, 0x3fd744fd, v191
	v_mul_f32_e32 v192, 0x3fd744fd, v192
	v_mul_f32_e32 v193, 0x3fd744fd, v193
	v_mul_f32_e32 v194, 0x3fd744fd, v194
	v_mul_f32_e32 v195, 0x3fd744fd, v195
	v_mul_f32_e32 v196, 0x3fd744fd, v196
	v_mul_f32_e32 v197, 0x3fd744fd, v197
	v_mul_f32_e32 v198, 0x3fd744fd, v198
	v_mul_f32_e32 v199, 0x3fd744fd, v199
	v_mul_f32_e32 v200, 0x3fd744fd, v200
	v_mul_f32_e32 v201, 0x3fd744fd, v201
	v_mul_f32_e32 v202, 0x3fd744fd, v202
	v_mul_f32_e32 v203, 0x3fd744fd, v203
	v_mul_f32_e32 v224, 0x3fd744fd, v224
	v_mul_f32_e32 v225, 0x3fd744fd, v225
	v_mul_f32_e32 v226, 0x3fd744fd, v226
	v_mul_f32_e32 v227, 0x3fd744fd, v227
	v_mul_f32_e32 v228, 0x3fd744fd, v228
	v_mul_f32_e32 v229, 0x3fd744fd, v229
	v_mul_f32_e32 v230, 0x3fd744fd, v230
	v_mul_f32_e32 v231, 0x3fd744fd, v231
	v_fmac_f32_e32 v174, v58, v241
	v_fmac_f32_e32 v175, v24, v242
	v_fmac_f32_e32 v176, v42, v243
	v_fmac_f32_e32 v177, v8, v151
	v_fmac_f32_e32 v184, v59, v241
	v_fmac_f32_e32 v185, v25, v242
	v_fmac_f32_e32 v186, v43, v243
	v_fmac_f32_e32 v187, v9, v151
	v_fmac_f32_e32 v188, v60, v241
	v_fmac_f32_e32 v189, v26, v242
	v_fmac_f32_e32 v190, v44, v243
	v_fmac_f32_e32 v191, v10, v151
	v_fmac_f32_e32 v192, v61, v241
	v_fmac_f32_e32 v193, v27, v242
	v_fmac_f32_e32 v194, v45, v243
	v_fmac_f32_e32 v195, v11, v151
	v_fmac_f32_e32 v196, v62, v241
	v_fmac_f32_e32 v197, v28, v242
	v_fmac_f32_e32 v198, v46, v243
	v_fmac_f32_e32 v199, v12, v151
	v_fmac_f32_e32 v200, v63, v241
	v_fmac_f32_e32 v201, v29, v242
	v_fmac_f32_e32 v202, v47, v243
	v_fmac_f32_e32 v203, v13, v151
	v_fmac_f32_e32 v224, v64, v241
	v_fmac_f32_e32 v225, v30, v242
	v_fmac_f32_e32 v226, v48, v243
	v_fmac_f32_e32 v227, v14, v151
	v_fmac_f32_e32 v228, v65, v241
	v_fmac_f32_e32 v229, v31, v242
	v_fmac_f32_e32 v230, v49, v243
	v_fmac_f32_e32 v231, v15, v151
	global_store_dword v130, v174, s[48:49]
	global_store_dword v130, v175, s[48:49] offset:128
	global_store_dword v130, v176, s[48:49] offset:256
	global_store_dword v130, v177, s[48:49] offset:384
	global_store_dword v131, v184, s[48:49]
	global_store_dword v131, v185, s[48:49] offset:128
	global_store_dword v131, v186, s[48:49] offset:256
	global_store_dword v131, v187, s[48:49] offset:384
	global_store_dword v132, v188, s[48:49]
	global_store_dword v132, v189, s[48:49] offset:128
	global_store_dword v132, v190, s[48:49] offset:256
	global_store_dword v132, v191, s[48:49] offset:384
	global_store_dword v133, v192, s[48:49]
	global_store_dword v133, v193, s[48:49] offset:128
	global_store_dword v133, v194, s[48:49] offset:256
	global_store_dword v133, v195, s[48:49] offset:384
	global_store_dword v134, v196, s[48:49]
	global_store_dword v134, v197, s[48:49] offset:128
	global_store_dword v134, v198, s[48:49] offset:256
	global_store_dword v134, v199, s[48:49] offset:384
	global_store_dword v135, v200, s[48:49]
	global_store_dword v135, v201, s[48:49] offset:128
	global_store_dword v135, v202, s[48:49] offset:256
	global_store_dword v135, v203, s[48:49] offset:384
	global_store_dword v136, v224, s[48:49]
	global_store_dword v136, v225, s[48:49] offset:128
	global_store_dword v136, v226, s[48:49] offset:256
	global_store_dword v136, v227, s[48:49] offset:384
	global_store_dword v137, v228, s[48:49]
	global_store_dword v137, v229, s[48:49] offset:128
	global_store_dword v137, v230, s[48:49] offset:256
	global_store_dword v137, v231, s[48:49] offset:384
	s_cbranch_scc1 .LBB0_940

.LBB0_1696:
	s_add_i32 s7, s3, 1
	s_cmp_lt_u32 s3, 31
	s_cselect_b32 s3, s7, s3
	s_lshl_b32 s16, s3, 6
	s_lshl_b64 s[14:15], s[16:17], 1
	s_barrier
	s_waitcnt vmcnt(0)
	ds_write_b128 v204, v[174:177]
	ds_write_b128 v204, v[170:173] offset:4608
	ds_write_b128 v204, v[166:169] offset:9216
	ds_write_b128 v204, v[162:165] offset:13824
	ds_write_b128 v204, v[158:161] offset:18432
	ds_write_b128 v204, v[154:157] offset:23040
	ds_write_b128 v204, v[150:153] offset:27648
	ds_write_b128 v204, v[146:149] offset:32256
	ds_write_b128 v204, v[142:145] offset:36864
	ds_write_b128 v204, v[134:137] offset:41472
	ds_write_b128 v204, v[130:133] offset:46080
	ds_write_b128 v204, v[138:141] offset:50688
	v_lshl_add_u64 v[130:131], v[178:179], 0, s[14:15]
	s_add_u32 s100, s14, 0x20000
	s_addc_u32 s101, s15, 0
	v_lshl_add_u64 v[132:133], v[178:179], 0, s[100:101]
	s_add_u32 s100, s100, 0x20000
	s_addc_u32 s101, s101, 0
	v_lshl_add_u64 v[134:135], v[178:179], 0, s[100:101]
	s_add_u32 s100, s100, 0x20000
	s_addc_u32 s101, s101, 0
	v_lshl_add_u64 v[136:137], v[178:179], 0, s[100:101]
	s_add_u32 s100, s100, 0x20000
	s_addc_u32 s101, s101, 0
	v_lshl_add_u64 v[138:139], v[178:179], 0, s[100:101]
	s_add_u32 s100, s100, 0x20000
	s_addc_u32 s101, s101, 0
	v_lshl_add_u64 v[140:141], v[178:179], 0, s[100:101]
	s_add_u32 s100, s100, 0x20000
	s_addc_u32 s101, s101, 0
	v_lshl_add_u64 v[142:143], v[178:179], 0, s[100:101]
	s_add_u32 s100, s100, 0x20000
	s_addc_u32 s101, s101, 0
	v_lshl_add_u64 v[144:145], v[178:179], 0, s[100:101]
	s_waitcnt lgkmcnt(0)
	s_barrier
	v_lshl_add_u64 v[224:225], v[180:181], 0, s[14:15]
	s_add_u32 s100, s14, 0x20000
	s_addc_u32 s101, s15, 0
	v_lshl_add_u64 v[226:227], v[180:181], 0, s[100:101]
	s_add_u32 s100, s100, 0x20000
	s_addc_u32 s101, s101, 0
	v_lshl_add_u64 v[228:229], v[180:181], 0, s[100:101]
	s_add_u32 s100, s100, 0x20000
	s_addc_u32 s101, s101, 0
	v_lshl_add_u64 v[230:231], v[180:181], 0, s[100:101]
	global_load_dwordx4 v[174:177], v[130:131], off
	global_load_dwordx4 v[170:173], v[132:133], off
	global_load_dwordx4 v[166:169], v[134:135], off
	global_load_dwordx4 v[162:165], v[136:137], off
	global_load_dwordx4 v[158:161], v[138:139], off
	global_load_dwordx4 v[154:157], v[140:141], off
	global_load_dwordx4 v[150:153], v[142:143], off
	global_load_dwordx4 v[146:149], v[144:145], off
	global_load_dwordx4 v[142:145], v[224:225], off
	global_load_dwordx4 v[134:137], v[226:227], off
	global_load_dwordx4 v[130:133], v[228:229], off
	global_load_dwordx4 v[138:141], v[230:231], off
	ds_read_b128 v[224:227], v182
	ds_read_b128 v[228:231], v183 offset:36864
	ds_read_b128 v[232:235], v183 offset:41472
	ds_read_b128 v[184:187], v182 offset:4608
	ds_read_b128 v[236:239], v183 offset:46080
	ds_read_b128 v[240:243], v183 offset:50688
	s_waitcnt lgkmcnt(4)
	v_mfma_f32_32x32x16_bf16 v[114:129], v[224:227], v[228:231], v[114:129]
	ds_read_b128 v[188:191], v183 offset:36896
	ds_read_b128 v[192:195], v183 offset:41504
	s_waitcnt lgkmcnt(5)
	v_mfma_f32_32x32x16_bf16 v[82:97], v[224:227], v[232:235], v[82:97]
	ds_read_b128 v[196:199], v183 offset:46112
	ds_read_b128 v[200:203], v183 offset:50720
	s_waitcnt lgkmcnt(5)
	v_mfma_f32_32x32x16_bf16 v[98:113], v[224:227], v[236:239], v[98:113]
	s_waitcnt lgkmcnt(4)
	v_mfma_f32_32x32x16_bf16 v[66:81], v[224:227], v[240:243], v[66:81]
	ds_read_b128 v[224:227], v182 offset:32
	v_mfma_f32_32x32x16_bf16 v[50:65], v[184:187], v[228:231], v[50:65]
	v_mfma_f32_32x32x16_bf16 v[16:31], v[184:187], v[232:235], v[16:31]
	v_mfma_f32_32x32x16_bf16 v[34:49], v[184:187], v[236:239], v[34:49]
	v_mfma_f32_32x32x16_bf16 v[0:15], v[184:187], v[240:243], v[0:15]
	ds_read_b128 v[184:187], v182 offset:4640
	s_waitcnt lgkmcnt(1)
	v_mfma_f32_32x32x16_bf16 v[114:129], v[224:227], v[188:191], v[114:129]
	ds_read_b128 v[228:231], v183 offset:36928
	ds_read_b128 v[232:235], v183 offset:41536
	v_mfma_f32_32x32x16_bf16 v[82:97], v[224:227], v[192:195], v[82:97]
	ds_read_b128 v[236:239], v183 offset:46144
	ds_read_b128 v[240:243], v183 offset:50752
	v_mfma_f32_32x32x16_bf16 v[98:113], v[224:227], v[196:199], v[98:113]
	v_mfma_f32_32x32x16_bf16 v[66:81], v[224:227], v[200:203], v[66:81]
	ds_read_b128 v[224:227], v182 offset:64
	s_waitcnt lgkmcnt(5)
	v_mfma_f32_32x32x16_bf16 v[50:65], v[184:187], v[188:191], v[50:65]
	v_mfma_f32_32x32x16_bf16 v[16:31], v[184:187], v[192:195], v[16:31]
	v_mfma_f32_32x32x16_bf16 v[34:49], v[184:187], v[196:199], v[34:49]
	v_mfma_f32_32x32x16_bf16 v[0:15], v[184:187], v[200:203], v[0:15]
	ds_read_b128 v[184:187], v182 offset:4672
	s_waitcnt lgkmcnt(1)
	v_mfma_f32_32x32x16_bf16 v[114:129], v[224:227], v[228:231], v[114:129]
	ds_read_b128 v[188:191], v183 offset:36960
	ds_read_b128 v[192:195], v183 offset:41568
	v_mfma_f32_32x32x16_bf16 v[82:97], v[224:227], v[232:235], v[82:97]
	ds_read_b128 v[196:199], v183 offset:46176
	ds_read_b128 v[200:203], v183 offset:50784
	v_mfma_f32_32x32x16_bf16 v[98:113], v[224:227], v[236:239], v[98:113]
	v_mfma_f32_32x32x16_bf16 v[66:81], v[224:227], v[240:243], v[66:81]
	ds_read_b128 v[224:227], v182 offset:96
	s_waitcnt lgkmcnt(5)
	v_mfma_f32_32x32x16_bf16 v[50:65], v[184:187], v[228:231], v[50:65]
	v_mfma_f32_32x32x16_bf16 v[16:31], v[184:187], v[232:235], v[16:31]
	v_mfma_f32_32x32x16_bf16 v[34:49], v[184:187], v[236:239], v[34:49]
	v_mfma_f32_32x32x16_bf16 v[0:15], v[184:187], v[240:243], v[0:15]
	ds_read_b128 v[184:187], v182 offset:4704
	s_waitcnt lgkmcnt(1)
	v_mfma_f32_32x32x16_bf16 v[114:129], v[224:227], v[188:191], v[114:129]
	v_mfma_f32_32x32x16_bf16 v[82:97], v[224:227], v[192:195], v[82:97]
	v_mfma_f32_32x32x16_bf16 v[98:113], v[224:227], v[196:199], v[98:113]
	v_mfma_f32_32x32x16_bf16 v[66:81], v[224:227], v[200:203], v[66:81]
	s_waitcnt lgkmcnt(0)
	v_mfma_f32_32x32x16_bf16 v[50:65], v[184:187], v[188:191], v[50:65]
	v_mfma_f32_32x32x16_bf16 v[16:31], v[184:187], v[192:195], v[16:31]
	v_mfma_f32_32x32x16_bf16 v[34:49], v[184:187], v[196:199], v[34:49]
	v_mfma_f32_32x32x16_bf16 v[0:15], v[184:187], v[200:203], v[0:15]
	s_mov_b32 s3, s7
	s_cmp_lg_u32 s7, 32
	s_cbranch_scc1 .LBB0_1696
	s_lshl_b32 s3, s6, 7
	s_lshr_b32 s6, s13, 24
	s_add_i32 s6, s12, s6
	s_lshr_b32 s6, s6, 8
	s_add_i32 s6, s6, s10
	v_mov_b32_e32 v32, v206
	s_barrier
	s_mulk_i32 s6, 0x1800
	s_ashr_i32 s7, s6, 31
	s_waitcnt vmcnt(1)
	v_and_b32_e32 v131, 0xffffffc0, v32
	v_lshrrev_b32_e32 v132, 3, v32
	v_readlane_b32 s36, v248, 46
	v_and_or_b32 v130, v32, 31, s3
	v_and_or_b32 v32, v132, 4, v131
	s_lshl_b64 s[6:7], s[6:7], 2
	v_readlane_b32 s40, v248, 50
	v_lshl_add_u32 v132, s2, 8, v32
	v_readlane_b32 s41, v248, 51
	s_add_u32 s6, s40, s6
	v_ashrrev_i32_e32 v133, 31, v132
	s_addc_u32 s7, s41, s7
	v_ashrrev_i32_e32 v131, 31, v130
	v_lshlrev_b64 v[136:137], 10, v[132:133]
	s_add_u32 s6, s6, 0x2000
	v_lshl_add_u64 v[136:137], v[136:137], 0, v[130:131]
	s_addc_u32 s7, s7, 0
	s_waitcnt vmcnt(0)
	v_lshlrev_b64 v[138:139], 2, v[136:137]
	v_lshl_add_u64 v[134:135], v[130:131], 2, s[6:7]
	v_lshl_add_u64 v[136:137], s[0:1], 0, v[138:139]
	v_readlane_b32 s48, v248, 58
	v_readlane_b32 s49, v248, 59
	v_writelane_b32 v251, s16, 29
	v_readlane_b32 s37, v248, 47
	v_readlane_b32 s38, v248, 48
	v_writelane_b32 v251, s17, 30
	v_readlane_b32 s39, v248, 49
	v_readlane_b32 s2, v251, 24
	s_add_i32 s11, s11, s2
	s_cmpk_lt_i32 s11, 0x200
	v_readlane_b32 s42, v248, 52
	v_readlane_b32 s43, v248, 53
	v_readlane_b32 s44, v248, 54
	v_readlane_b32 s45, v248, 55
	v_readlane_b32 s46, v248, 56
	v_readlane_b32 s47, v248, 57
	v_readlane_b32 s50, v248, 60
	v_readlane_b32 s51, v248, 61
	v_readlane_b32 s3, v251, 25
	s_waitcnt vmcnt(0)
	v_lshlrev_b32_e32 v240, 2, v130
	v_lshl_add_u32 v240, v132, 12, v240
	s_nop 2
	global_load_dword v241, v[134:135], off
	global_load_dword v242, v[134:135], off offset:128
	global_load_dword v243, v[134:135], off offset:256
	global_load_dword v151, v[134:135], off offset:384
	v_mov_b32_e32 v232, v240
	v_add_u32_e32 v233, 0x1000, v240
	v_add_u32_e32 v234, 0x2000, v240
	v_add_u32_e32 v235, 0x3000, v240
	v_add_u32_e32 v236, 0x8000, v240
	v_add_u32_e32 v237, 0x9000, v240
	v_add_u32_e32 v238, 0xa000, v240
	v_add_u32_e32 v239, 0xb000, v240
	global_load_dword v138, v232, s[0:1]
	global_load_dword v139, v232, s[0:1] offset:128
	global_load_dword v140, v232, s[0:1] offset:256
	global_load_dword v141, v232, s[0:1] offset:384
	global_load_dword v142, v233, s[0:1]
	global_load_dword v143, v233, s[0:1] offset:128
	global_load_dword v144, v233, s[0:1] offset:256
	global_load_dword v145, v233, s[0:1] offset:384
	global_load_dword v146, v234, s[0:1]
	global_load_dword v147, v234, s[0:1] offset:128
	global_load_dword v152, v234, s[0:1] offset:256
	global_load_dword v153, v234, s[0:1] offset:384
	global_load_dword v154, v235, s[0:1]
	global_load_dword v155, v235, s[0:1] offset:128
	global_load_dword v156, v235, s[0:1] offset:256
	global_load_dword v157, v235, s[0:1] offset:384
	global_load_dword v158, v236, s[0:1]
	global_load_dword v159, v236, s[0:1] offset:128
	global_load_dword v160, v236, s[0:1] offset:256
	global_load_dword v161, v236, s[0:1] offset:384
	global_load_dword v162, v237, s[0:1]
	global_load_dword v163, v237, s[0:1] offset:128
	global_load_dword v164, v237, s[0:1] offset:256
	global_load_dword v165, v237, s[0:1] offset:384
	global_load_dword v166, v238, s[0:1]
	global_load_dword v167, v238, s[0:1] offset:128
	global_load_dword v168, v238, s[0:1] offset:256
	global_load_dword v169, v238, s[0:1] offset:384
	global_load_dword v170, v239, s[0:1]
	global_load_dword v171, v239, s[0:1] offset:128
	global_load_dword v172, v239, s[0:1] offset:256
	global_load_dword v173, v239, s[0:1] offset:384
	v_add_u32_e32 v130, 0x10000, v240
	v_add_u32_e32 v131, 0x11000, v240
	v_add_u32_e32 v132, 0x12000, v240
	v_add_u32_e32 v133, 0x13000, v240
	v_add_u32_e32 v134, 0x18000, v240
	v_add_u32_e32 v135, 0x19000, v240
	v_add_u32_e32 v136, 0x1a000, v240
	v_add_u32_e32 v137, 0x1b000, v240
	global_load_dword v174, v130, s[0:1]
	global_load_dword v175, v130, s[0:1] offset:128
	global_load_dword v176, v130, s[0:1] offset:256
	global_load_dword v177, v130, s[0:1] offset:384
	global_load_dword v184, v131, s[0:1]
	global_load_dword v185, v131, s[0:1] offset:128
	global_load_dword v186, v131, s[0:1] offset:256
	global_load_dword v187, v131, s[0:1] offset:384
	global_load_dword v188, v132, s[0:1]
	global_load_dword v189, v132, s[0:1] offset:128
	global_load_dword v190, v132, s[0:1] offset:256
	global_load_dword v191, v132, s[0:1] offset:384
	global_load_dword v192, v133, s[0:1]
	global_load_dword v193, v133, s[0:1] offset:128
	global_load_dword v194, v133, s[0:1] offset:256
	global_load_dword v195, v133, s[0:1] offset:384
	global_load_dword v196, v134, s[0:1]
	global_load_dword v197, v134, s[0:1] offset:128
	global_load_dword v198, v134, s[0:1] offset:256
	global_load_dword v199, v134, s[0:1] offset:384
	global_load_dword v200, v135, s[0:1]
	global_load_dword v201, v135, s[0:1] offset:128
	global_load_dword v202, v135, s[0:1] offset:256
	global_load_dword v203, v135, s[0:1] offset:384
	global_load_dword v224, v136, s[0:1]
	global_load_dword v225, v136, s[0:1] offset:128
	global_load_dword v226, v136, s[0:1] offset:256
	global_load_dword v227, v136, s[0:1] offset:384
	global_load_dword v228, v137, s[0:1]
	global_load_dword v229, v137, s[0:1] offset:128
	global_load_dword v230, v137, s[0:1] offset:256
	global_load_dword v231, v137, s[0:1] offset:384
	s_waitcnt vmcnt(32)
	v_mul_f32_e32 v138, 0x3fd744fd, v138
	v_mul_f32_e32 v139, 0x3fd744fd, v139
	v_mul_f32_e32 v140, 0x3fd744fd, v140
	v_mul_f32_e32 v141, 0x3fd744fd, v141
	v_mul_f32_e32 v142, 0x3fd744fd, v142
	v_mul_f32_e32 v143, 0x3fd744fd, v143
	v_mul_f32_e32 v144, 0x3fd744fd, v144
	v_mul_f32_e32 v145, 0x3fd744fd, v145
	v_mul_f32_e32 v146, 0x3fd744fd, v146
	v_mul_f32_e32 v147, 0x3fd744fd, v147
	v_mul_f32_e32 v152, 0x3fd744fd, v152
	v_mul_f32_e32 v153, 0x3fd744fd, v153
	v_mul_f32_e32 v154, 0x3fd744fd, v154
	v_mul_f32_e32 v155, 0x3fd744fd, v155
	v_mul_f32_e32 v156, 0x3fd744fd, v156
	v_mul_f32_e32 v157, 0x3fd744fd, v157
	v_mul_f32_e32 v158, 0x3fd744fd, v158
	v_mul_f32_e32 v159, 0x3fd744fd, v159
	v_mul_f32_e32 v160, 0x3fd744fd, v160
	v_mul_f32_e32 v161, 0x3fd744fd, v161
	v_mul_f32_e32 v162, 0x3fd744fd, v162
	v_mul_f32_e32 v163, 0x3fd744fd, v163
	v_mul_f32_e32 v164, 0x3fd744fd, v164
	v_mul_f32_e32 v165, 0x3fd744fd, v165
	v_mul_f32_e32 v166, 0x3fd744fd, v166
	v_mul_f32_e32 v167, 0x3fd744fd, v167
	v_mul_f32_e32 v168, 0x3fd744fd, v168
	v_mul_f32_e32 v169, 0x3fd744fd, v169
	v_mul_f32_e32 v170, 0x3fd744fd, v170
	v_mul_f32_e32 v171, 0x3fd744fd, v171
	v_mul_f32_e32 v172, 0x3fd744fd, v172
	v_mul_f32_e32 v173, 0x3fd744fd, v173
	v_fmac_f32_e32 v138, v114, v241
	v_fmac_f32_e32 v139, v82, v242
	v_fmac_f32_e32 v140, v98, v243
	v_fmac_f32_e32 v141, v66, v151
	v_fmac_f32_e32 v142, v115, v241
	v_fmac_f32_e32 v143, v83, v242
	v_fmac_f32_e32 v144, v99, v243
	v_fmac_f32_e32 v145, v67, v151
	v_fmac_f32_e32 v146, v116, v241
	v_fmac_f32_e32 v147, v84, v242
	v_fmac_f32_e32 v152, v100, v243
	v_fmac_f32_e32 v153, v68, v151
	v_fmac_f32_e32 v154, v117, v241
	v_fmac_f32_e32 v155, v85, v242
	v_fmac_f32_e32 v156, v101, v243
	v_fmac_f32_e32 v157, v69, v151
	v_fmac_f32_e32 v158, v118, v241
	v_fmac_f32_e32 v159, v86, v242
	v_fmac_f32_e32 v160, v102, v243
	v_fmac_f32_e32 v161, v70, v151
	v_fmac_f32_e32 v162, v119, v241
	v_fmac_f32_e32 v163, v87, v242
	v_fmac_f32_e32 v164, v103, v243
	v_fmac_f32_e32 v165, v71, v151
	v_fmac_f32_e32 v166, v120, v241
	v_fmac_f32_e32 v167, v88, v242
	v_fmac_f32_e32 v168, v104, v243
	v_fmac_f32_e32 v169, v72, v151
	v_fmac_f32_e32 v170, v121, v241
	v_fmac_f32_e32 v171, v89, v242
	v_fmac_f32_e32 v172, v105, v243
	v_fmac_f32_e32 v173, v73, v151
	global_store_dword v232, v138, s[48:49]
	global_store_dword v232, v139, s[48:49] offset:128
	global_store_dword v232, v140, s[48:49] offset:256
	global_store_dword v232, v141, s[48:49] offset:384
	global_store_dword v233, v142, s[48:49]
	global_store_dword v233, v143, s[48:49] offset:128
	global_store_dword v233, v144, s[48:49] offset:256
	global_store_dword v233, v145, s[48:49] offset:384
	global_store_dword v234, v146, s[48:49]
	global_store_dword v234, v147, s[48:49] offset:128
	global_store_dword v234, v152, s[48:49] offset:256
	global_store_dword v234, v153, s[48:49] offset:384
	global_store_dword v235, v154, s[48:49]
	global_store_dword v235, v155, s[48:49] offset:128
	global_store_dword v235, v156, s[48:49] offset:256
	global_store_dword v235, v157, s[48:49] offset:384
	global_store_dword v236, v158, s[48:49]
	global_store_dword v236, v159, s[48:49] offset:128
	global_store_dword v236, v160, s[48:49] offset:256
	global_store_dword v236, v161, s[48:49] offset:384
	global_store_dword v237, v162, s[48:49]
	global_store_dword v237, v163, s[48:49] offset:128
	global_store_dword v237, v164, s[48:49] offset:256
	global_store_dword v237, v165, s[48:49] offset:384
	global_store_dword v238, v166, s[48:49]
	global_store_dword v238, v167, s[48:49] offset:128
	global_store_dword v238, v168, s[48:49] offset:256
	global_store_dword v238, v169, s[48:49] offset:384
	global_store_dword v239, v170, s[48:49]
	global_store_dword v239, v171, s[48:49] offset:128
	global_store_dword v239, v172, s[48:49] offset:256
	global_store_dword v239, v173, s[48:49] offset:384
	v_add_u32_e32 v232, 0x20000, v240
	v_add_u32_e32 v233, 0x21000, v240
	v_add_u32_e32 v234, 0x22000, v240
	v_add_u32_e32 v235, 0x23000, v240
	v_add_u32_e32 v236, 0x28000, v240
	v_add_u32_e32 v237, 0x29000, v240
	v_add_u32_e32 v238, 0x2a000, v240
	v_add_u32_e32 v239, 0x2b000, v240
	global_load_dword v138, v232, s[0:1]
	global_load_dword v139, v232, s[0:1] offset:128
	global_load_dword v140, v232, s[0:1] offset:256
	global_load_dword v141, v232, s[0:1] offset:384
	global_load_dword v142, v233, s[0:1]
	global_load_dword v143, v233, s[0:1] offset:128
	global_load_dword v144, v233, s[0:1] offset:256
	global_load_dword v145, v233, s[0:1] offset:384
	global_load_dword v146, v234, s[0:1]
	global_load_dword v147, v234, s[0:1] offset:128
	global_load_dword v152, v234, s[0:1] offset:256
	global_load_dword v153, v234, s[0:1] offset:384
	global_load_dword v154, v235, s[0:1]
	global_load_dword v155, v235, s[0:1] offset:128
	global_load_dword v156, v235, s[0:1] offset:256
	global_load_dword v157, v235, s[0:1] offset:384
	global_load_dword v158, v236, s[0:1]
	global_load_dword v159, v236, s[0:1] offset:128
	global_load_dword v160, v236, s[0:1] offset:256
	global_load_dword v161, v236, s[0:1] offset:384
	global_load_dword v162, v237, s[0:1]
	global_load_dword v163, v237, s[0:1] offset:128
	global_load_dword v164, v237, s[0:1] offset:256
	global_load_dword v165, v237, s[0:1] offset:384
	global_load_dword v166, v238, s[0:1]
	global_load_dword v167, v238, s[0:1] offset:128
	global_load_dword v168, v238, s[0:1] offset:256
	global_load_dword v169, v238, s[0:1] offset:384
	global_load_dword v170, v239, s[0:1]
	global_load_dword v171, v239, s[0:1] offset:128
	global_load_dword v172, v239, s[0:1] offset:256
	global_load_dword v173, v239, s[0:1] offset:384
	s_waitcnt vmcnt(63)
	v_mul_f32_e32 v174, 0x3fd744fd, v174
	v_mul_f32_e32 v175, 0x3fd744fd, v175
	v_mul_f32_e32 v176, 0x3fd744fd, v176
	v_mul_f32_e32 v177, 0x3fd744fd, v177
	v_mul_f32_e32 v184, 0x3fd744fd, v184
	v_mul_f32_e32 v185, 0x3fd744fd, v185
	v_mul_f32_e32 v186, 0x3fd744fd, v186
	v_mul_f32_e32 v187, 0x3fd744fd, v187
	v_mul_f32_e32 v188, 0x3fd744fd, v188
	v_mul_f32_e32 v189, 0x3fd744fd, v189
	v_mul_f32_e32 v190, 0x3fd744fd, v190
	v_mul_f32_e32 v191, 0x3fd744fd, v191
	v_mul_f32_e32 v192, 0x3fd744fd, v192
	v_mul_f32_e32 v193, 0x3fd744fd, v193
	v_mul_f32_e32 v194, 0x3fd744fd, v194
	v_mul_f32_e32 v195, 0x3fd744fd, v195
	v_mul_f32_e32 v196, 0x3fd744fd, v196
	v_mul_f32_e32 v197, 0x3fd744fd, v197
	v_mul_f32_e32 v198, 0x3fd744fd, v198
	v_mul_f32_e32 v199, 0x3fd744fd, v199
	v_mul_f32_e32 v200, 0x3fd744fd, v200
	v_mul_f32_e32 v201, 0x3fd744fd, v201
	v_mul_f32_e32 v202, 0x3fd744fd, v202
	v_mul_f32_e32 v203, 0x3fd744fd, v203
	v_mul_f32_e32 v224, 0x3fd744fd, v224
	v_mul_f32_e32 v225, 0x3fd744fd, v225
	v_mul_f32_e32 v226, 0x3fd744fd, v226
	v_mul_f32_e32 v227, 0x3fd744fd, v227
	v_mul_f32_e32 v228, 0x3fd744fd, v228
	v_mul_f32_e32 v229, 0x3fd744fd, v229
	v_mul_f32_e32 v230, 0x3fd744fd, v230
	v_mul_f32_e32 v231, 0x3fd744fd, v231
	v_fmac_f32_e32 v174, v122, v241
	v_fmac_f32_e32 v175, v90, v242
	v_fmac_f32_e32 v176, v106, v243
	v_fmac_f32_e32 v177, v74, v151
	v_fmac_f32_e32 v184, v123, v241
	v_fmac_f32_e32 v185, v91, v242
	v_fmac_f32_e32 v186, v107, v243
	v_fmac_f32_e32 v187, v75, v151
	v_fmac_f32_e32 v188, v124, v241
	v_fmac_f32_e32 v189, v92, v242
	v_fmac_f32_e32 v190, v108, v243
	v_fmac_f32_e32 v191, v76, v151
	v_fmac_f32_e32 v192, v125, v241
	v_fmac_f32_e32 v193, v93, v242
	v_fmac_f32_e32 v194, v109, v243
	v_fmac_f32_e32 v195, v77, v151
	v_fmac_f32_e32 v196, v126, v241
	v_fmac_f32_e32 v197, v94, v242
	v_fmac_f32_e32 v198, v110, v243
	v_fmac_f32_e32 v199, v78, v151
	v_fmac_f32_e32 v200, v127, v241
	v_fmac_f32_e32 v201, v95, v242
	v_fmac_f32_e32 v202, v111, v243
	v_fmac_f32_e32 v203, v79, v151
	v_fmac_f32_e32 v224, v128, v241
	v_fmac_f32_e32 v225, v96, v242
	v_fmac_f32_e32 v226, v112, v243
	v_fmac_f32_e32 v227, v80, v151
	v_fmac_f32_e32 v228, v129, v241
	v_fmac_f32_e32 v229, v97, v242
	v_fmac_f32_e32 v230, v113, v243
	v_fmac_f32_e32 v231, v81, v151
	global_store_dword v130, v174, s[48:49]
	global_store_dword v130, v175, s[48:49] offset:128
	global_store_dword v130, v176, s[48:49] offset:256
	global_store_dword v130, v177, s[48:49] offset:384
	global_store_dword v131, v184, s[48:49]
	global_store_dword v131, v185, s[48:49] offset:128
	global_store_dword v131, v186, s[48:49] offset:256
	global_store_dword v131, v187, s[48:49] offset:384
	global_store_dword v132, v188, s[48:49]
	global_store_dword v132, v189, s[48:49] offset:128
	global_store_dword v132, v190, s[48:49] offset:256
	global_store_dword v132, v191, s[48:49] offset:384
	global_store_dword v133, v192, s[48:49]
	global_store_dword v133, v193, s[48:49] offset:128
	global_store_dword v133, v194, s[48:49] offset:256
	global_store_dword v133, v195, s[48:49] offset:384
	global_store_dword v134, v196, s[48:49]
	global_store_dword v134, v197, s[48:49] offset:128
	global_store_dword v134, v198, s[48:49] offset:256
	global_store_dword v134, v199, s[48:49] offset:384
	global_store_dword v135, v200, s[48:49]
	global_store_dword v135, v201, s[48:49] offset:128
	global_store_dword v135, v202, s[48:49] offset:256
	global_store_dword v135, v203, s[48:49] offset:384
	global_store_dword v136, v224, s[48:49]
	global_store_dword v136, v225, s[48:49] offset:128
	global_store_dword v136, v226, s[48:49] offset:256
	global_store_dword v136, v227, s[48:49] offset:384
	global_store_dword v137, v228, s[48:49]
	global_store_dword v137, v229, s[48:49] offset:128
	global_store_dword v137, v230, s[48:49] offset:256
	global_store_dword v137, v231, s[48:49] offset:384
	v_add_u32_e32 v130, 0x30000, v240
	v_add_u32_e32 v131, 0x31000, v240
	v_add_u32_e32 v132, 0x32000, v240
	v_add_u32_e32 v133, 0x33000, v240
	v_add_u32_e32 v134, 0x38000, v240
	v_add_u32_e32 v135, 0x39000, v240
	v_add_u32_e32 v136, 0x3a000, v240
	v_add_u32_e32 v137, 0x3b000, v240
	global_load_dword v174, v130, s[0:1]
	global_load_dword v175, v130, s[0:1] offset:128
	global_load_dword v176, v130, s[0:1] offset:256
	global_load_dword v177, v130, s[0:1] offset:384
	global_load_dword v184, v131, s[0:1]
	global_load_dword v185, v131, s[0:1] offset:128
	global_load_dword v186, v131, s[0:1] offset:256
	global_load_dword v187, v131, s[0:1] offset:384
	global_load_dword v188, v132, s[0:1]
	global_load_dword v189, v132, s[0:1] offset:128
	global_load_dword v190, v132, s[0:1] offset:256
	global_load_dword v191, v132, s[0:1] offset:384
	global_load_dword v192, v133, s[0:1]
	global_load_dword v193, v133, s[0:1] offset:128
	global_load_dword v194, v133, s[0:1] offset:256
	global_load_dword v195, v133, s[0:1] offset:384
	global_load_dword v196, v134, s[0:1]
	global_load_dword v197, v134, s[0:1] offset:128
	global_load_dword v198, v134, s[0:1] offset:256
	global_load_dword v199, v134, s[0:1] offset:384
	global_load_dword v200, v135, s[0:1]
	global_load_dword v201, v135, s[0:1] offset:128
	global_load_dword v202, v135, s[0:1] offset:256
	global_load_dword v203, v135, s[0:1] offset:384
	global_load_dword v224, v136, s[0:1]
	global_load_dword v225, v136, s[0:1] offset:128
	global_load_dword v226, v136, s[0:1] offset:256
	global_load_dword v227, v136, s[0:1] offset:384
	global_load_dword v228, v137, s[0:1]
	global_load_dword v229, v137, s[0:1] offset:128
	global_load_dword v230, v137, s[0:1] offset:256
	global_load_dword v231, v137, s[0:1] offset:384
	s_waitcnt vmcnt(63)
	v_mul_f32_e32 v138, 0x3fd744fd, v138
	v_mul_f32_e32 v139, 0x3fd744fd, v139
	v_mul_f32_e32 v140, 0x3fd744fd, v140
	v_mul_f32_e32 v141, 0x3fd744fd, v141
	v_mul_f32_e32 v142, 0x3fd744fd, v142
	v_mul_f32_e32 v143, 0x3fd744fd, v143
	v_mul_f32_e32 v144, 0x3fd744fd, v144
	v_mul_f32_e32 v145, 0x3fd744fd, v145
	v_mul_f32_e32 v146, 0x3fd744fd, v146
	v_mul_f32_e32 v147, 0x3fd744fd, v147
	v_mul_f32_e32 v152, 0x3fd744fd, v152
	v_mul_f32_e32 v153, 0x3fd744fd, v153
	v_mul_f32_e32 v154, 0x3fd744fd, v154
	v_mul_f32_e32 v155, 0x3fd744fd, v155
	v_mul_f32_e32 v156, 0x3fd744fd, v156
	v_mul_f32_e32 v157, 0x3fd744fd, v157
	v_mul_f32_e32 v158, 0x3fd744fd, v158
	v_mul_f32_e32 v159, 0x3fd744fd, v159
	v_mul_f32_e32 v160, 0x3fd744fd, v160
	v_mul_f32_e32 v161, 0x3fd744fd, v161
	v_mul_f32_e32 v162, 0x3fd744fd, v162
	v_mul_f32_e32 v163, 0x3fd744fd, v163
	v_mul_f32_e32 v164, 0x3fd744fd, v164
	v_mul_f32_e32 v165, 0x3fd744fd, v165
	v_mul_f32_e32 v166, 0x3fd744fd, v166
	v_mul_f32_e32 v167, 0x3fd744fd, v167
	v_mul_f32_e32 v168, 0x3fd744fd, v168
	v_mul_f32_e32 v169, 0x3fd744fd, v169
	v_mul_f32_e32 v170, 0x3fd744fd, v170
	v_mul_f32_e32 v171, 0x3fd744fd, v171
	v_mul_f32_e32 v172, 0x3fd744fd, v172
	v_mul_f32_e32 v173, 0x3fd744fd, v173
	v_fmac_f32_e32 v138, v50, v241
	v_fmac_f32_e32 v139, v16, v242
	v_fmac_f32_e32 v140, v34, v243
	v_fmac_f32_e32 v141, v0, v151
	v_fmac_f32_e32 v142, v51, v241
	v_fmac_f32_e32 v143, v17, v242
	v_fmac_f32_e32 v144, v35, v243
	v_fmac_f32_e32 v145, v1, v151
	v_fmac_f32_e32 v146, v52, v241
	v_fmac_f32_e32 v147, v18, v242
	v_fmac_f32_e32 v152, v36, v243
	v_fmac_f32_e32 v153, v2, v151
	v_fmac_f32_e32 v154, v53, v241
	v_fmac_f32_e32 v155, v19, v242
	v_fmac_f32_e32 v156, v37, v243
	v_fmac_f32_e32 v157, v3, v151
	v_fmac_f32_e32 v158, v54, v241
	v_fmac_f32_e32 v159, v20, v242
	v_fmac_f32_e32 v160, v38, v243
	v_fmac_f32_e32 v161, v4, v151
	v_fmac_f32_e32 v162, v55, v241
	v_fmac_f32_e32 v163, v21, v242
	v_fmac_f32_e32 v164, v39, v243
	v_fmac_f32_e32 v165, v5, v151
	v_fmac_f32_e32 v166, v56, v241
	v_fmac_f32_e32 v167, v22, v242
	v_fmac_f32_e32 v168, v40, v243
	v_fmac_f32_e32 v169, v6, v151
	v_fmac_f32_e32 v170, v57, v241
	v_fmac_f32_e32 v171, v23, v242
	v_fmac_f32_e32 v172, v41, v243
	v_fmac_f32_e32 v173, v7, v151
	global_store_dword v232, v138, s[48:49]
	global_store_dword v232, v139, s[48:49] offset:128
	global_store_dword v232, v140, s[48:49] offset:256
	global_store_dword v232, v141, s[48:49] offset:384
	global_store_dword v233, v142, s[48:49]
	global_store_dword v233, v143, s[48:49] offset:128
	global_store_dword v233, v144, s[48:49] offset:256
	global_store_dword v233, v145, s[48:49] offset:384
	global_store_dword v234, v146, s[48:49]
	global_store_dword v234, v147, s[48:49] offset:128
	global_store_dword v234, v152, s[48:49] offset:256
	global_store_dword v234, v153, s[48:49] offset:384
	global_store_dword v235, v154, s[48:49]
	global_store_dword v235, v155, s[48:49] offset:128
	global_store_dword v235, v156, s[48:49] offset:256
	global_store_dword v235, v157, s[48:49] offset:384
	global_store_dword v236, v158, s[48:49]
	global_store_dword v236, v159, s[48:49] offset:128
	global_store_dword v236, v160, s[48:49] offset:256
	global_store_dword v236, v161, s[48:49] offset:384
	global_store_dword v237, v162, s[48:49]
	global_store_dword v237, v163, s[48:49] offset:128
	global_store_dword v237, v164, s[48:49] offset:256
	global_store_dword v237, v165, s[48:49] offset:384
	global_store_dword v238, v166, s[48:49]
	global_store_dword v238, v167, s[48:49] offset:128
	global_store_dword v238, v168, s[48:49] offset:256
	global_store_dword v238, v169, s[48:49] offset:384
	global_store_dword v239, v170, s[48:49]
	global_store_dword v239, v171, s[48:49] offset:128
	global_store_dword v239, v172, s[48:49] offset:256
	global_store_dword v239, v173, s[48:49] offset:384
	s_waitcnt vmcnt(32)
	v_mul_f32_e32 v174, 0x3fd744fd, v174
	v_mul_f32_e32 v175, 0x3fd744fd, v175
	v_mul_f32_e32 v176, 0x3fd744fd, v176
	v_mul_f32_e32 v177, 0x3fd744fd, v177
	v_mul_f32_e32 v184, 0x3fd744fd, v184
	v_mul_f32_e32 v185, 0x3fd744fd, v185
	v_mul_f32_e32 v186, 0x3fd744fd, v186
	v_mul_f32_e32 v187, 0x3fd744fd, v187
	v_mul_f32_e32 v188, 0x3fd744fd, v188
	v_mul_f32_e32 v189, 0x3fd744fd, v189
	v_mul_f32_e32 v190, 0x3fd744fd, v190
	v_mul_f32_e32 v191, 0x3fd744fd, v191
	v_mul_f32_e32 v192, 0x3fd744fd, v192
	v_mul_f32_e32 v193, 0x3fd744fd, v193
	v_mul_f32_e32 v194, 0x3fd744fd, v194
	v_mul_f32_e32 v195, 0x3fd744fd, v195
	v_mul_f32_e32 v196, 0x3fd744fd, v196
	v_mul_f32_e32 v197, 0x3fd744fd, v197
	v_mul_f32_e32 v198, 0x3fd744fd, v198
	v_mul_f32_e32 v199, 0x3fd744fd, v199
	v_mul_f32_e32 v200, 0x3fd744fd, v200
	v_mul_f32_e32 v201, 0x3fd744fd, v201
	v_mul_f32_e32 v202, 0x3fd744fd, v202
	v_mul_f32_e32 v203, 0x3fd744fd, v203
	v_mul_f32_e32 v224, 0x3fd744fd, v224
	v_mul_f32_e32 v225, 0x3fd744fd, v225
	v_mul_f32_e32 v226, 0x3fd744fd, v226
	v_mul_f32_e32 v227, 0x3fd744fd, v227
	v_mul_f32_e32 v228, 0x3fd744fd, v228
	v_mul_f32_e32 v229, 0x3fd744fd, v229
	v_mul_f32_e32 v230, 0x3fd744fd, v230
	v_mul_f32_e32 v231, 0x3fd744fd, v231
	v_fmac_f32_e32 v174, v58, v241
	v_fmac_f32_e32 v175, v24, v242
	v_fmac_f32_e32 v176, v42, v243
	v_fmac_f32_e32 v177, v8, v151
	v_fmac_f32_e32 v184, v59, v241
	v_fmac_f32_e32 v185, v25, v242
	v_fmac_f32_e32 v186, v43, v243
	v_fmac_f32_e32 v187, v9, v151
	v_fmac_f32_e32 v188, v60, v241
	v_fmac_f32_e32 v189, v26, v242
	v_fmac_f32_e32 v190, v44, v243
	v_fmac_f32_e32 v191, v10, v151
	v_fmac_f32_e32 v192, v61, v241
	v_fmac_f32_e32 v193, v27, v242
	v_fmac_f32_e32 v194, v45, v243
	v_fmac_f32_e32 v195, v11, v151
	v_fmac_f32_e32 v196, v62, v241
	v_fmac_f32_e32 v197, v28, v242
	v_fmac_f32_e32 v198, v46, v243
	v_fmac_f32_e32 v199, v12, v151
	v_fmac_f32_e32 v200, v63, v241
	v_fmac_f32_e32 v201, v29, v242
	v_fmac_f32_e32 v202, v47, v243
	v_fmac_f32_e32 v203, v13, v151
	v_fmac_f32_e32 v224, v64, v241
	v_fmac_f32_e32 v225, v30, v242
	v_fmac_f32_e32 v226, v48, v243
	v_fmac_f32_e32 v227, v14, v151
	v_fmac_f32_e32 v228, v65, v241
	v_fmac_f32_e32 v229, v31, v242
	v_fmac_f32_e32 v230, v49, v243
	v_fmac_f32_e32 v231, v15, v151
	global_store_dword v130, v174, s[48:49]
	global_store_dword v130, v175, s[48:49] offset:128
	global_store_dword v130, v176, s[48:49] offset:256
	global_store_dword v130, v177, s[48:49] offset:384
	global_store_dword v131, v184, s[48:49]
	global_store_dword v131, v185, s[48:49] offset:128
	global_store_dword v131, v186, s[48:49] offset:256
	global_store_dword v131, v187, s[48:49] offset:384
	global_store_dword v132, v188, s[48:49]
	global_store_dword v132, v189, s[48:49] offset:128
	global_store_dword v132, v190, s[48:49] offset:256
	global_store_dword v132, v191, s[48:49] offset:384
	global_store_dword v133, v192, s[48:49]
	global_store_dword v133, v193, s[48:49] offset:128
	global_store_dword v133, v194, s[48:49] offset:256
	global_store_dword v133, v195, s[48:49] offset:384
	global_store_dword v134, v196, s[48:49]
	global_store_dword v134, v197, s[48:49] offset:128
	global_store_dword v134, v198, s[48:49] offset:256
	global_store_dword v134, v199, s[48:49] offset:384
	global_store_dword v135, v200, s[48:49]
	global_store_dword v135, v201, s[48:49] offset:128
	global_store_dword v135, v202, s[48:49] offset:256
	global_store_dword v135, v203, s[48:49] offset:384
	global_store_dword v136, v224, s[48:49]
	global_store_dword v136, v225, s[48:49] offset:128
	global_store_dword v136, v226, s[48:49] offset:256
	global_store_dword v136, v227, s[48:49] offset:384
	global_store_dword v137, v228, s[48:49]
	global_store_dword v137, v229, s[48:49] offset:128
	global_store_dword v137, v230, s[48:49] offset:256
	global_store_dword v137, v231, s[48:49] offset:384
	s_cbranch_scc1 .LBB0_1692
